# v181 plus two steps' scan outputs per ds_write2_b32
# baseline (speedup 1.0000x reference)
.LBB0_398:
	s_or_b64 exec, exec, s[38:39]
	v_lshl_or_b32 v2, s8, 10, v142
	v_mov_b32_e32 v3, v0
	v_lshl_add_u64 v[2:3], v[68:69], 0, v[2:3]
	global_load_ushort v212, v[2:3], off
	global_load_ushort v213, v[2:3], off offset:1024
	global_load_ushort v214, v[2:3], off offset:2048
	global_load_ushort v215, v[2:3], off offset:3072
	v_add_u32_e32 v91, v143, v102
	ds_read_b128 v[92:95], v91 offset:12544
	ds_read_b128 v[164:167], v91 offset:13056
	ds_read_b128 v[216:219], v91 offset:13568
	ds_read_b128 v[220:223], v146 offset:12544
	ds_read_b128 v[224:227], v91 offset:14592
	ds_read_b128 v[228:231], v91 offset:15104
	ds_read_b128 v[244:247], v91 offset:15616
	ds_read_b128 v[248:251], v147 offset:12544
	s_andn2_b64 vcc, exec, s[50:51]
	s_waitcnt lgkmcnt(7)
	v_mfma_f32_16x16x32_bf16 v[92:95], v[12:15], v[92:95], 0
	s_waitcnt lgkmcnt(6)
	v_mfma_f32_16x16x32_bf16 v[164:167], v[12:15], v[164:167], 0
	s_waitcnt lgkmcnt(5)
	v_mfma_f32_16x16x32_bf16 v[216:219], v[12:15], v[216:219], 0
	s_waitcnt lgkmcnt(4)
	v_mfma_f32_16x16x32_bf16 v[220:223], v[12:15], v[220:223], 0
	s_waitcnt lgkmcnt(3)
	v_mfma_f32_16x16x32_bf16 v[224:227], v[12:15], v[224:227], 0
	s_waitcnt lgkmcnt(2)
	v_mfma_f32_16x16x32_bf16 v[228:231], v[12:15], v[228:231], 0
	s_waitcnt lgkmcnt(1)
	v_mfma_f32_16x16x32_bf16 v[244:247], v[12:15], v[244:247], 0
	s_waitcnt lgkmcnt(0)
	v_mfma_f32_16x16x32_bf16 v[248:251], v[12:15], v[248:251], 0
	s_nop 1
	v_permlane32_swap_b32_e32 v92, v216
	v_permlane32_swap_b32_e32 v164, v220
	v_permlane32_swap_b32_e32 v93, v217
	v_permlane32_swap_b32_e32 v165, v221
	v_permlane32_swap_b32_e32 v94, v218
	v_permlane32_swap_b32_e32 v166, v222
	v_permlane32_swap_b32_e32 v95, v219
	v_permlane32_swap_b32_e32 v167, v223
	v_permlane16_swap_b32_e32 v92, v164
	v_permlane16_swap_b32_e32 v216, v220
	v_permlane16_swap_b32_e32 v93, v165
	v_permlane16_swap_b32_e32 v217, v221
	v_permlane16_swap_b32_e32 v94, v166
	v_permlane16_swap_b32_e32 v218, v222
	v_permlane16_swap_b32_e32 v95, v167
	v_permlane16_swap_b32_e32 v219, v223
	v_permlane32_swap_b32_e32 v224, v244
	v_permlane32_swap_b32_e32 v228, v248
	v_permlane32_swap_b32_e32 v225, v245
	v_permlane32_swap_b32_e32 v229, v249
	v_permlane32_swap_b32_e32 v226, v246
	v_permlane32_swap_b32_e32 v230, v250
	v_permlane32_swap_b32_e32 v227, v247
	v_permlane32_swap_b32_e32 v231, v251
	v_permlane16_swap_b32_e32 v224, v228
	v_permlane16_swap_b32_e32 v244, v248
	v_permlane16_swap_b32_e32 v225, v229
	v_permlane16_swap_b32_e32 v245, v249
	v_permlane16_swap_b32_e32 v226, v230
	v_permlane16_swap_b32_e32 v246, v250
	v_permlane16_swap_b32_e32 v227, v231
	v_permlane16_swap_b32_e32 v247, v251
	s_waitcnt lgkmcnt(0)
	v_lshl_add_u32 v91, v98, 1, v141
	v_add_u32_e32 v96, 0x2000, v91
	v_add_u32_e32 v97, 0x2440, v91
	v_add_u32_e32 v159, 0x2880, v91
	v_add_u32_e32 v91, 0x2cc0, v91
	v_fma_f32 v14, -v64, v61, v92
	v_fma_f32 v15, v64, v60, v224
	v_pk_fma_f32 v[60:61], v[56:57], v[60:61], v[14:15] op_sel_hi:[0,1,1]
	v_cvt_pk_bf16_f32 v12, v60, v61
	v_fma_f32 v14, -v64, v61, v93
	v_fma_f32 v15, v64, v60, v225
	v_pk_fma_f32 v[60:61], v[56:57], v[60:61], v[14:15] op_sel_hi:[0,1,1]
	v_cvt_pk_bf16_f32 v13, v60, v61
	ds_write2_b32 v96, v12, v13 offset0:0 offset1:68
	v_fma_f32 v14, -v64, v61, v94
	v_fma_f32 v15, v64, v60, v226
	v_pk_fma_f32 v[60:61], v[56:57], v[60:61], v[14:15] op_sel_hi:[0,1,1]
	v_cvt_pk_bf16_f32 v12, v60, v61
	v_fma_f32 v14, -v64, v61, v95
	v_fma_f32 v15, v64, v60, v227
	v_pk_fma_f32 v[60:61], v[56:57], v[60:61], v[14:15] op_sel_hi:[0,1,1]
	v_cvt_pk_bf16_f32 v13, v60, v61
	ds_write2_b32 v96, v12, v13 offset0:136 offset1:204
	v_fma_f32 v14, -v64, v61, v164
	v_fma_f32 v15, v64, v60, v228
	v_pk_fma_f32 v[60:61], v[56:57], v[60:61], v[14:15] op_sel_hi:[0,1,1]
	v_cvt_pk_bf16_f32 v12, v60, v61
	v_fma_f32 v14, -v64, v61, v165
	v_fma_f32 v15, v64, v60, v229
	v_pk_fma_f32 v[60:61], v[56:57], v[60:61], v[14:15] op_sel_hi:[0,1,1]
	v_cvt_pk_bf16_f32 v13, v60, v61
	ds_write2_b32 v97, v12, v13 offset0:0 offset1:68
	v_fma_f32 v14, -v64, v61, v166
	v_fma_f32 v15, v64, v60, v230
	v_pk_fma_f32 v[60:61], v[56:57], v[60:61], v[14:15] op_sel_hi:[0,1,1]
	v_cvt_pk_bf16_f32 v12, v60, v61
	v_fma_f32 v14, -v64, v61, v167
	v_fma_f32 v15, v64, v60, v231
	v_pk_fma_f32 v[60:61], v[56:57], v[60:61], v[14:15] op_sel_hi:[0,1,1]
	v_cvt_pk_bf16_f32 v13, v60, v61
	ds_write2_b32 v97, v12, v13 offset0:136 offset1:204
	v_fma_f32 v14, -v64, v61, v216
	v_fma_f32 v15, v64, v60, v244
	v_pk_fma_f32 v[60:61], v[56:57], v[60:61], v[14:15] op_sel_hi:[0,1,1]
	v_cvt_pk_bf16_f32 v12, v60, v61
	v_fma_f32 v14, -v64, v61, v217
	v_fma_f32 v15, v64, v60, v245
	v_pk_fma_f32 v[60:61], v[56:57], v[60:61], v[14:15] op_sel_hi:[0,1,1]
	v_cvt_pk_bf16_f32 v13, v60, v61
	ds_write2_b32 v159, v12, v13 offset0:0 offset1:68
	v_fma_f32 v14, -v64, v61, v218
	v_fma_f32 v15, v64, v60, v246
	v_pk_fma_f32 v[60:61], v[56:57], v[60:61], v[14:15] op_sel_hi:[0,1,1]
	v_cvt_pk_bf16_f32 v12, v60, v61
	v_fma_f32 v14, -v64, v61, v219
	v_fma_f32 v15, v64, v60, v247
	v_pk_fma_f32 v[60:61], v[56:57], v[60:61], v[14:15] op_sel_hi:[0,1,1]
	v_cvt_pk_bf16_f32 v13, v60, v61
	ds_write2_b32 v159, v12, v13 offset0:136 offset1:204
	v_fma_f32 v14, -v64, v61, v220
	v_fma_f32 v15, v64, v60, v248
	v_pk_fma_f32 v[60:61], v[56:57], v[60:61], v[14:15] op_sel_hi:[0,1,1]
	v_cvt_pk_bf16_f32 v12, v60, v61
	v_fma_f32 v14, -v64, v61, v221
	v_fma_f32 v15, v64, v60, v249
	v_pk_fma_f32 v[60:61], v[56:57], v[60:61], v[14:15] op_sel_hi:[0,1,1]
	v_cvt_pk_bf16_f32 v13, v60, v61
	ds_write2_b32 v91, v12, v13 offset0:0 offset1:68
	v_fma_f32 v14, -v64, v61, v222
	v_fma_f32 v15, v64, v60, v250
	v_pk_fma_f32 v[60:61], v[56:57], v[60:61], v[14:15] op_sel_hi:[0,1,1]
	v_cvt_pk_bf16_f32 v12, v60, v61
	v_fma_f32 v14, -v64, v61, v223
	v_fma_f32 v15, v64, v60, v251
	v_pk_fma_f32 v[60:61], v[56:57], v[60:61], v[14:15] op_sel_hi:[0,1,1]
	v_cvt_pk_bf16_f32 v13, v60, v61
	ds_write2_b32 v91, v12, v13 offset0:136 offset1:204
	s_waitcnt lgkmcnt(0)
	ds_read_b128 v[12:15], v144 offset:8192
	ds_read_b128 v[92:95], v145 offset:16640
	ds_read_b128 v[216:219], v144 offset:8256
	ds_read_b128 v[220:223], v145 offset:16704
	ds_read_b128 v[224:227], v144 offset:8320
	ds_read_b128 v[228:231], v145 offset:16768
	ds_read_b128 v[244:247], v144 offset:8384
	ds_read_b128 v[248:251], v145 offset:16832
	s_waitcnt lgkmcnt(6)
	v_mfma_f32_16x16x32_bf16 v[12:15], v[12:15], v[92:95], 0
	s_waitcnt lgkmcnt(4)
	v_mfma_f32_16x16x32_bf16 v[12:15], v[216:219], v[220:223], v[12:15]
	s_waitcnt lgkmcnt(2)
	v_mfma_f32_16x16x32_bf16 v[12:15], v[224:227], v[228:231], v[12:15]
	s_waitcnt lgkmcnt(0)
	v_mfma_f32_16x16x32_bf16 v[12:15], v[244:247], v[248:251], v[12:15]
	s_nop 7
	s_waitcnt vmcnt(0)
	v_lshlrev_b32_e32 v88, 16, v212
	v_lshlrev_b32_e32 v89, 16, v213
	v_lshlrev_b32_e32 v90, 16, v214
	v_lshlrev_b32_e32 v91, 16, v215
	v_pk_fma_f32 v[12:13], v[148:149], v[88:89], v[12:13] op_sel_hi:[0,1,1]
	v_pk_fma_f32 v[14:15], v[148:149], v[90:91], v[14:15] op_sel_hi:[0,1,1]
	v_mov_b32_e32 v88, 0x3dd2d3e8
	v_mov_b32_e32 v90, 0x40135761
	v_pk_mul_f32 v[92:93], v[12:13], v[12:13]
	v_pk_mul_f32 v[94:95], v[14:15], v[14:15]
	v_pk_fma_f32 v[92:93], v[92:93], v[88:89], v[90:91] op_sel_hi:[1,0,0]
	v_pk_fma_f32 v[94:95], v[94:95], v[88:89], v[90:91] op_sel_hi:[1,0,0]
	v_pk_mul_f32 v[92:93], v[92:93], v[12:13]
	v_pk_mul_f32 v[94:95], v[94:95], v[14:15]
	v_mov_b32_e32 v88, 1.0
	v_exp_f32_e32 v92, v92
	v_exp_f32_e32 v93, v93
	v_exp_f32_e32 v94, v94
	v_exp_f32_e32 v95, v95
	s_nop 0
	v_pk_add_f32 v[92:93], v[92:93], v[88:89] op_sel_hi:[1,0]
	v_pk_add_f32 v[94:95], v[94:95], v[88:89] op_sel_hi:[1,0]
	v_rcp_f32_e32 v92, v92
	v_rcp_f32_e32 v93, v93
	v_rcp_f32_e32 v94, v94
	v_rcp_f32_e32 v95, v95
	s_nop 0
	v_pk_fma_f32 v[12:13], v[12:13], v[92:93], v[12:13] neg_lo:[1,0,0] neg_hi:[1,0,0]
	v_pk_fma_f32 v[14:15], v[14:15], v[94:95], v[14:15] neg_lo:[1,0,0] neg_hi:[1,0,0]
	v_cvt_pk_bf16_f32 v12, v12, v13
	v_cvt_pk_bf16_f32 v14, v14, v15
	global_store_short v[2:3], v12, off
	global_store_short_d16_hi v[2:3], v12, off offset:1024
	global_store_short v[2:3], v14, off offset:2048
	global_store_short_d16_hi v[2:3], v14, off offset:3072
	s_waitcnt lgkmcnt(0)
	v_lshlrev_b32_e32 v1, 2, v128
	s_cbranch_vccnz .LBB0_408
	s_waitcnt vmcnt(4)
	v_lshlrev_b32_e32 v16, 16, v176
	v_lshlrev_b32_e32 v30, 16, v177
	v_lshlrev_b32_e32 v32, 16, v178
	v_lshlrev_b32_e32 v36, 16, v179
	v_lshlrev_b32_e32 v17, 16, v180
	v_lshlrev_b32_e32 v26, 16, v181
	v_lshlrev_b32_e32 v27, 16, v182
	v_lshlrev_b32_e32 v28, 16, v183
	v_lshlrev_b32_e32 v29, 16, v184
	v_lshlrev_b32_e32 v31, 16, v185
	v_lshlrev_b32_e32 v33, 16, v186
	v_lshlrev_b32_e32 v37, 16, v187
	v_lshlrev_b32_e32 v34, 16, v188
	v_lshlrev_b32_e32 v35, 16, v189
	v_lshlrev_b32_e32 v38, 16, v190
	v_lshlrev_b32_e32 v39, 16, v195
	v_lshlrev_b32_e32 v40, 16, v197
	v_lshlrev_b32_e32 v43, 16, v198
	v_lshlrev_b32_e32 v42, 16, v199
	v_lshlrev_b32_e32 v45, 16, v200
	v_lshlrev_b32_e32 v44, 16, v201
	v_lshlrev_b32_e32 v46, 16, v203
	v_lshlrev_b32_e32 v49, 16, v204
	v_lshlrev_b32_e32 v48, 16, v205
	v_lshlrev_b32_e32 v41, 16, v196
	v_lshlrev_b32_e32 v47, 16, v202
	v_lshlrev_b32_e32 v51, 16, v206
	v_lshlrev_b32_e32 v50, 16, v207
	v_lshlrev_b32_e32 v53, 16, v191
	v_lshlrev_b32_e32 v52, 16, v193
	v_lshlrev_b32_e32 v55, 16, v192
	v_lshlrev_b32_e32 v54, 16, v194
	v_add_f32_e32 v88, v155, v35
	v_mul_f32_e32 v88, 0xbfb8aa3b, v88
	v_exp_f32_e32 v88, v88
	v_pk_add_f32 v[12:13], v[32:33], v[26:27] neg_lo:[0,1] neg_hi:[0,1]
	v_pk_add_f32 v[2:3], v[30:31], v[16:17] neg_lo:[0,1] neg_hi:[0,1]
	v_fma_f32 v13, v150, v13, v27
	v_add_f32_e32 v88, 1.0, v88
	v_rcp_f32_e32 v88, v88
	v_mul_f32_e32 v92, v157, v13
	v_fma_f32 v3, v149, v3, v17
	s_bitcmp1_b32 s3, 0
	v_mul_f32_e32 v89, 0xbf6002b1, v88
	v_cmp_gt_f32_e32 vcc, s85, v89
	s_cselect_b32 s8, 0x5000, 0
	v_mov_b32_e32 v94, v0
	v_cndmask_b32_e32 v89, 0, v239, vcc
	v_fmac_f32_e32 v89, 0xbf6002b1, v88
	v_exp_f32_e32 v88, v89
	v_cndmask_b32_e32 v89, 0, v236, vcc
	s_add_i32 s9, s8, 0
	s_mul_i32 s8, s3, 0xab
	v_ldexp_f32 v90, v88, v89
	v_add_f32_e32 v88, v154, v39
	v_mul_f32_e32 v88, 0xbfb8aa3b, v88
	v_exp_f32_e32 v88, v88
	v_mov_b32_e32 v89, v0
	s_bfe_u32 s8, s8, 0x70009
	s_mul_i32 s8, s8, 3
	v_add_f32_e32 v88, 1.0, v88
	v_rcp_f32_e32 v91, v88
	v_mul_f32_e32 v88, v92, v92
	s_sub_i32 s8, s3, s8
	s_and_b32 s8, s8, 0xff
	v_mov_b32_dpp v89, v88 quad_perm:[1,0,3,2] row_mask:0xf bank_mask:0xf
	v_fmac_f32_e32 v89, v92, v92
	s_mulk_i32 s8, 0x1100
	s_add_i32 s8, s8, 0
	v_add_f32_dpp v88, v89, v89 quad_perm:[2,3,0,1] row_mask:0xf bank_mask:0xf bound_ctrl:1
	v_pk_add_f32 v[14:15], v[36:37], v[28:29] neg_lo:[0,1] neg_hi:[0,1]
	s_nop 0
	v_add_f32_dpp v88, v88, v88 row_half_mirror row_mask:0xf bank_mask:0xf bound_ctrl:1
	v_fma_f32 v15, v151, v15, v29
	s_nop 0
	v_add_f32_dpp v88, v88, v88 row_mirror row_mask:0xf bank_mask:0xf bound_ctrl:1
	s_nop 0
	s_nop 1
	v_add_f32_dpp v88, v88, v88 row_bcast:15 row_mask:0xa bank_mask:0xf
	s_nop 1
	v_add_f32_dpp v88, v88, v88 row_bcast:31 row_mask:0xc bank_mask:0xf
	s_nop 0
	v_readlane_b32 s26, v88, 63
	s_nop 1
	v_mov_b32_e32 v88, s26
	v_add_f32_e32 v88, 0x2b8cbccc, v88
	v_cmp_gt_f32_e32 vcc, s82, v88
	v_mul_f32_e32 v89, 0x4b800000, v88
	s_nop 0
	v_cndmask_b32_e32 v88, v88, v89, vcc
	v_rsq_f32_e32 v88, v88
	s_nop 0
	v_mul_f32_e32 v89, 0x45800000, v88
	v_cndmask_b32_e32 v88, v88, v89, vcc
	v_add_f32_e32 v89, -1.0, v91
	v_fma_f32 v89, v158, v89, 1.0
	v_mul_f32_e32 v13, v89, v13
	v_mul_f32_e32 v89, v13, v3
	v_mul_f32_e32 v93, v156, v89
	v_mul_f32_e64 v88, v92, -v88
	s_nop 0
	v_mov_b32_dpp v94, v93 quad_perm:[1,0,3,2] row_mask:0xf bank_mask:0xf
	v_fmac_f32_e32 v94, v156, v89
	s_nop 1
	v_add_f32_dpp v89, v94, v94 quad_perm:[2,3,0,1] row_mask:0xf bank_mask:0xf bound_ctrl:1
	s_nop 1
	v_add_f32_dpp v89, v89, v89 row_half_mirror row_mask:0xf bank_mask:0xf bound_ctrl:1
	s_nop 1
	v_add_f32_dpp v89, v89, v89 row_mirror row_mask:0xf bank_mask:0xf bound_ctrl:1
	s_nop 0
	s_nop 1
	v_add_f32_dpp v89, v89, v89 row_bcast:15 row_mask:0xa bank_mask:0xf
	s_nop 1
	v_add_f32_dpp v89, v89, v89 row_bcast:31 row_mask:0xc bank_mask:0xf
	s_nop 0
	v_readlane_b32 s38, v89, 63
	v_add_u32_e32 v89, s9, v1
	ds_write2st64_b32 v89, v90, v88 offset1:16
	v_mul_f32_e64 v88, v91, -v88
	ds_write2st64_b32 v89, v88, v13 offset0:32 offset1:48
	ds_write_b32 v89, v3 offset:16384
	v_add_u32_e32 v3, s8, v1
	ds_write_b32 v3, v15 offset:40960
	s_and_saveexec_b64 s[50:51], s[44:45]
	s_cbranch_execz .LBB0_401
	s_lshl_b32 s24, s96, 2
	s_add_i32 s24, s8, s24
	v_mov_b32_e32 v13, s24
	v_mov_b32_e32 v3, s38
	ds_write_b32 v13, v3 offset:45056
